# forgetting-attention: second-round head chosen by runtime rank of fox_b_f (heaviest head paired with lightest) instead of fixed 15-h
# baseline (speedup 1.0000x reference)
; template <int DQK, bool FOX>
; __device__ __forceinline__ void causal_attn_phase(LAS unsigned char* lds, const bf16_t* Q, int qpitch, const bf16_t* K1, const bf16_t* K2, const bf16_t* V, bf16_t* O, const float* cum2, const float* rope_cs_tab, const float* fox_ct) {
;     ...
;     for (int u = blockIdx.x; u < 512; u += gridDim.x) {
;         const int rnd = u >> 8, bb = u & 255, head = bb & 15, qb = rnd == 0 ? 31 - (bb >> 4) : (bb >> 4);
.LBB0_2741:
	s_or_b64 exec, exec, s[0:1]
	s_mov_b64 s[0:1], s[76:77]
	v_mov_b32_e32 v177, v204
	s_waitcnt lgkmcnt(0)
	s_barrier
	s_and_b64 vcc, exec, s[92:93]
	v_readfirstlane_b32 s2, v177
	s_cbranch_vccnz .LBB0_2775
	s_load_dwordx2 s[98:99], s[0:1], 0x98
	v_and_b32_e32 v6, 15, v202
	v_lshlrev_b32_e32 v0, 2, v6
	v_mov_b32_e32 v8, 0
	s_waitcnt lgkmcnt(0)
	global_load_dword v7, v0, s[98:99]
	s_waitcnt vmcnt(0)
	v_readlane_b32 s100, v7, 0
	s_nop 1
	v_cmp_lt_f32_e32 vcc, s100, v7
	s_nop 1
	v_cndmask_b32_e64 v0, 0, 1, vcc
	v_cmp_eq_f32_e32 vcc, s100, v7
	s_nop 1
	v_cndmask_b32_e64 v2, 0, 1, vcc
	v_cmp_lt_u32_e32 vcc, 0, v6
	s_nop 1
	v_cndmask_b32_e32 v2, 0, v2, vcc
	v_add3_u32 v8, v8, v0, v2
	v_readlane_b32 s100, v7, 1
	s_nop 1
	v_cmp_lt_f32_e32 vcc, s100, v7
	s_nop 1
	v_cndmask_b32_e64 v0, 0, 1, vcc
	v_cmp_eq_f32_e32 vcc, s100, v7
	s_nop 1
	v_cndmask_b32_e64 v2, 0, 1, vcc
	v_cmp_lt_u32_e32 vcc, 1, v6
	s_nop 1
	v_cndmask_b32_e32 v2, 0, v2, vcc
	v_add3_u32 v8, v8, v0, v2
	v_readlane_b32 s100, v7, 2
	s_nop 1
	v_cmp_lt_f32_e32 vcc, s100, v7
	s_nop 1
	v_cndmask_b32_e64 v0, 0, 1, vcc
	v_cmp_eq_f32_e32 vcc, s100, v7
	s_nop 1
	v_cndmask_b32_e64 v2, 0, 1, vcc
	v_cmp_lt_u32_e32 vcc, 2, v6
	s_nop 1
	v_cndmask_b32_e32 v2, 0, v2, vcc
	v_add3_u32 v8, v8, v0, v2
	v_readlane_b32 s100, v7, 3
	s_nop 1
	v_cmp_lt_f32_e32 vcc, s100, v7
	s_nop 1
	v_cndmask_b32_e64 v0, 0, 1, vcc
	v_cmp_eq_f32_e32 vcc, s100, v7
	s_nop 1
	v_cndmask_b32_e64 v2, 0, 1, vcc
	v_cmp_lt_u32_e32 vcc, 3, v6
	s_nop 1
	v_cndmask_b32_e32 v2, 0, v2, vcc
	v_add3_u32 v8, v8, v0, v2
	v_readlane_b32 s100, v7, 4
	s_nop 1
	v_cmp_lt_f32_e32 vcc, s100, v7
	s_nop 1
	v_cndmask_b32_e64 v0, 0, 1, vcc
	v_cmp_eq_f32_e32 vcc, s100, v7
	s_nop 1
	v_cndmask_b32_e64 v2, 0, 1, vcc
	v_cmp_lt_u32_e32 vcc, 4, v6
	s_nop 1
	v_cndmask_b32_e32 v2, 0, v2, vcc
	v_add3_u32 v8, v8, v0, v2
	v_readlane_b32 s100, v7, 5
	s_nop 1
	v_cmp_lt_f32_e32 vcc, s100, v7
	s_nop 1
	v_cndmask_b32_e64 v0, 0, 1, vcc
	v_cmp_eq_f32_e32 vcc, s100, v7
	s_nop 1
	v_cndmask_b32_e64 v2, 0, 1, vcc
	v_cmp_lt_u32_e32 vcc, 5, v6
	s_nop 1
	v_cndmask_b32_e32 v2, 0, v2, vcc
	v_add3_u32 v8, v8, v0, v2
	v_readlane_b32 s100, v7, 6
	s_nop 1
	v_cmp_lt_f32_e32 vcc, s100, v7
	s_nop 1
	v_cndmask_b32_e64 v0, 0, 1, vcc
	v_cmp_eq_f32_e32 vcc, s100, v7
	s_nop 1
	v_cndmask_b32_e64 v2, 0, 1, vcc
	v_cmp_lt_u32_e32 vcc, 6, v6
	s_nop 1
	v_cndmask_b32_e32 v2, 0, v2, vcc
	v_add3_u32 v8, v8, v0, v2
	v_readlane_b32 s100, v7, 7
	s_nop 1
	v_cmp_lt_f32_e32 vcc, s100, v7
	s_nop 1
	v_cndmask_b32_e64 v0, 0, 1, vcc
	v_cmp_eq_f32_e32 vcc, s100, v7
	s_nop 1
	v_cndmask_b32_e64 v2, 0, 1, vcc
	v_cmp_lt_u32_e32 vcc, 7, v6
	s_nop 1
	v_cndmask_b32_e32 v2, 0, v2, vcc
	v_add3_u32 v8, v8, v0, v2
	v_readlane_b32 s100, v7, 8
	s_nop 1
	v_cmp_lt_f32_e32 vcc, s100, v7
	s_nop 1
	v_cndmask_b32_e64 v0, 0, 1, vcc
	v_cmp_eq_f32_e32 vcc, s100, v7
	s_nop 1
	v_cndmask_b32_e64 v2, 0, 1, vcc
	v_cmp_lt_u32_e32 vcc, 8, v6
	s_nop 1
	v_cndmask_b32_e32 v2, 0, v2, vcc
	v_add3_u32 v8, v8, v0, v2
	v_readlane_b32 s100, v7, 9
	s_nop 1
	v_cmp_lt_f32_e32 vcc, s100, v7
	s_nop 1
	v_cndmask_b32_e64 v0, 0, 1, vcc
	v_cmp_eq_f32_e32 vcc, s100, v7
	s_nop 1
	v_cndmask_b32_e64 v2, 0, 1, vcc
	v_cmp_lt_u32_e32 vcc, 9, v6
	s_nop 1
	v_cndmask_b32_e32 v2, 0, v2, vcc
	v_add3_u32 v8, v8, v0, v2
	v_readlane_b32 s100, v7, 10
	s_nop 1
	v_cmp_lt_f32_e32 vcc, s100, v7
	s_nop 1
	v_cndmask_b32_e64 v0, 0, 1, vcc
	v_cmp_eq_f32_e32 vcc, s100, v7
	s_nop 1
	v_cndmask_b32_e64 v2, 0, 1, vcc
	v_cmp_lt_u32_e32 vcc, 10, v6
	s_nop 1
	v_cndmask_b32_e32 v2, 0, v2, vcc
	v_add3_u32 v8, v8, v0, v2
	v_readlane_b32 s100, v7, 11
	s_nop 1
	v_cmp_lt_f32_e32 vcc, s100, v7
	s_nop 1
	v_cndmask_b32_e64 v0, 0, 1, vcc
	v_cmp_eq_f32_e32 vcc, s100, v7
	s_nop 1
	v_cndmask_b32_e64 v2, 0, 1, vcc
	v_cmp_lt_u32_e32 vcc, 11, v6
	s_nop 1
	v_cndmask_b32_e32 v2, 0, v2, vcc
	v_add3_u32 v8, v8, v0, v2
	v_readlane_b32 s100, v7, 12
	s_nop 1
	v_cmp_lt_f32_e32 vcc, s100, v7
	s_nop 1
	v_cndmask_b32_e64 v0, 0, 1, vcc
	v_cmp_eq_f32_e32 vcc, s100, v7
	s_nop 1
	v_cndmask_b32_e64 v2, 0, 1, vcc
	v_cmp_lt_u32_e32 vcc, 12, v6
	s_nop 1
	v_cndmask_b32_e32 v2, 0, v2, vcc
	v_add3_u32 v8, v8, v0, v2
	v_readlane_b32 s100, v7, 13
	s_nop 1
	v_cmp_lt_f32_e32 vcc, s100, v7
	s_nop 1
	v_cndmask_b32_e64 v0, 0, 1, vcc
	v_cmp_eq_f32_e32 vcc, s100, v7
	s_nop 1
	v_cndmask_b32_e64 v2, 0, 1, vcc
	v_cmp_lt_u32_e32 vcc, 13, v6
	s_nop 1
	v_cndmask_b32_e32 v2, 0, v2, vcc
	v_add3_u32 v8, v8, v0, v2
	v_readlane_b32 s100, v7, 14
	s_nop 1
	v_cmp_lt_f32_e32 vcc, s100, v7
	s_nop 1
	v_cndmask_b32_e64 v0, 0, 1, vcc
	v_cmp_eq_f32_e32 vcc, s100, v7
	s_nop 1
	v_cndmask_b32_e64 v2, 0, 1, vcc
	v_cmp_lt_u32_e32 vcc, 14, v6
	s_nop 1
	v_cndmask_b32_e32 v2, 0, v2, vcc
	v_add3_u32 v8, v8, v0, v2
	v_readlane_b32 s100, v7, 15
	s_nop 1
	v_cmp_lt_f32_e32 vcc, s100, v7
	s_nop 1
	v_cndmask_b32_e64 v0, 0, 1, vcc
	v_cmp_eq_f32_e32 vcc, s100, v7
	s_nop 1
	v_cndmask_b32_e64 v2, 0, 1, vcc
	v_cmp_lt_u32_e32 vcc, 15, v6
	s_nop 1
	v_cndmask_b32_e32 v2, 0, v2, vcc
	v_add3_u32 v8, v8, v0, v2
	v_lshlrev_b32_e32 v0, 2, v8
	ds_permute_b32 v2, v0, v6
	s_waitcnt lgkmcnt(0)
; #define LAS __attribute__((address_space(3)))
; template <int DQK, bool FOX>
; __device__ __forceinline__ void causal_attn_phase(LAS unsigned char* lds, const bf16_t* Q, int qpitch, const bf16_t* K1, const bf16_t* K2, const bf16_t* V, bf16_t* O, const float* cum2, const float* rope_cs_tab, const float* fox_ct) {
;     ...
;     const int tid = ltid(), lane = tid & 63, wid = __builtin_amdgcn_readfirstlane(tid >> 6), r32 = lane & 31, hi = lane >> 5;
;     for (int u = blockIdx.x; u < 512; u += gridDim.x) {
;         const int rnd = u >> 8, bb = u & 255, head = bb & 15, qb = rnd == 0 ? 31 - (bb >> 4) : (bb >> 4);
;         const int q0 = qb * 256, qrow = q0 + wid * 32 + r32;
;         bf16x8 qf[NKS];
;         { const bf16_t* qp = Q + (size_t)qrow * qpitch + head * DQK + hi * 8;
; #pragma unroll
;           for (int ks = 0; ks < NKS; ++ks) qf[ks] = *(const bf16x8*)(qp + ks * 16); }
;         if constexpr (DQK == 192) {
; #pragma unroll
;             for (int sidx = 0; sidx < 2; ++sidx) {
;                 const f32x4* csp = (const f32x4*)(rope_cs_tab + (size_t)qrow * 64 + (16 * sidx + 8 * hi) * 2);
; #pragma unroll
;                 for (int jj = 0; jj < 4; ++jj) { const f32x4 cs = csp[jj];
; #pragma unroll
;                     for (int e = 0; e < 2; ++e) { const int j = 2 * jj + e; const float c = e ? cs.z : cs.x, sn = e ? cs.w : cs.y;
;                         const float x1 = bf2f((unsigned short)qf[8 + sidx][j]), x2 = bf2f((unsigned short)qf[10 + sidx][j]);
;                         qf[8 + sidx][j] = (short)(cvtpk(x1 * c - x2 * sn, 0.f) & 0xffffu); qf[10 + sidx][j] = (short)(cvtpk(x2 * c + x1 * sn, 0.f) & 0xffffu); } }
;             }
;         }
;         LAS float* offs = (LAS float*)(lds + 2 * BUF);
;         if constexpr (FOX) {
;             if (wid == 0) { const float a = fox_ct[head * 128 + lane], b = fox_ct[head * 128 + 64 + lane]; float ia = a, ib = b;
; #pragma unroll
;                 for (int o_ = 1; o_ < 64; o_ <<= 1) { const float va = __shfl_up(ia, o_), vb = __shfl_up(ib, o_); if (lane >= o_) { ia += va; ib += vb; } }
;                 const float tota = __shfl(ia, 63);
;                 offs[lane] = ia - a; offs[64 + lane] = tota + (ib - b);
;                 float km = fmaxf(fox_ct[T + head * 128 + lane], fox_ct[T + head * 128 + 64 + lane]);
; #pragma unroll
;                 for (int o_ = 1; o_ < 64; o_ <<= 1) km = fmaxf(km, __shfl_xor(km, o_));
	v_lshl_or_b32 v247, v2, 8, v8
	v_and_b32_e32 v7, 64, v202
	v_xor_b32_e32 v6, 32, v202
	v_add_u32_e32 v8, 64, v7
	v_cmp_lt_i32_e32 vcc, v6, v8
	v_bfe_u32 v2, v177, 5, 1
	v_lshlrev_b32_e32 v0, 3, v2
	v_cndmask_b32_e32 v6, v202, v6, vcc
	v_lshlrev_b32_e32 v195, 2, v6
	v_lshlrev_b32_e32 v6, 4, v177
	v_and_b32_e32 v196, 0xf0, v6
	v_lshrrev_b32_e32 v6, 1, v177
	v_and_b32_e32 v200, 16, v6
	v_lshlrev_b32_e32 v176, 2, v2
	v_lshrrev_b32_e32 v2, 3, v177
	v_bfe_u32 v6, v177, 2, 2
	v_and_b32_e32 v192, 63, v177
	v_and_or_b32 v2, v2, 4, v6
	v_lshlrev_b32_e32 v3, 2, v192
	v_mul_u32_u24_e32 v201, 0x140, v2
	v_and_b32_e32 v2, 16, v177
	v_and_or_b32 v2, v3, 12, v2
	v_lshlrev_b32_e32 v203, 1, v2
	v_add_u32_e32 v2, -1, v202
	v_cmp_lt_i32_e32 vcc, v2, v7
	s_load_dwordx2 s[4:5], s[0:1], 0xd8
	v_lshlrev_b32_e32 v5, 3, v177
	v_cndmask_b32_e32 v2, v2, v202, vcc
	s_waitcnt vmcnt(9)
	v_lshlrev_b32_e32 v205, 2, v2
	v_add_u32_e32 v2, -2, v202
	v_cmp_lt_i32_e32 vcc, v2, v7
	s_waitcnt lgkmcnt(0)
	s_add_u32 s30, s4, 0x2d700000
	s_addc_u32 s31, s5, 0
	v_cndmask_b32_e32 v2, v2, v202, vcc
	v_lshlrev_b32_e32 v206, 2, v2
	v_add_u32_e32 v2, -4, v202
	v_cmp_lt_i32_e32 vcc, v2, v7
	s_add_u32 s0, s4, 0x30700000
	v_writelane_b32 v245, s0, 26
	v_cndmask_b32_e32 v2, v2, v202, vcc
	v_lshlrev_b32_e32 v207, 2, v2
	v_add_u32_e32 v2, -8, v202
	v_cmp_lt_i32_e32 vcc, v2, v7
	s_addc_u32 s0, s5, 0
	v_writelane_b32 v245, s0, 27
	v_cndmask_b32_e32 v2, v2, v202, vcc
	v_lshlrev_b32_e32 v208, 2, v2
	v_add_u32_e32 v2, -16, v202
	v_cmp_lt_i32_e32 vcc, v2, v7
	s_add_u32 s0, s4, 0x33700000
	v_writelane_b32 v245, s0, 28
	v_cndmask_b32_e32 v2, v2, v202, vcc
	v_lshlrev_b32_e32 v209, 2, v2
	v_subrev_u32_e32 v2, 32, v202
	v_cmp_lt_i32_e32 vcc, v2, v7
	s_addc_u32 s0, s5, 0
	s_add_u32 s28, s4, 0x39700000
	v_cndmask_b32_e32 v2, v2, v202, vcc
	s_waitcnt vmcnt(0)
	v_lshlrev_b32_e32 v210, 2, v2
	v_bfrev_b32_e32 v2, 0.5
	v_lshl_or_b32 v211, v202, 2, v2
	v_xor_b32_e32 v2, 1, v202
	v_cmp_lt_i32_e32 vcc, v2, v8
	s_addc_u32 s29, s5, 0
	v_writelane_b32 v245, s0, 29
	v_cndmask_b32_e32 v2, v202, v2, vcc
	v_lshlrev_b32_e32 v212, 2, v2
	v_xor_b32_e32 v2, 2, v202
	v_cmp_lt_i32_e32 vcc, v2, v8
	s_add_u32 s0, s4, 0.5
	s_addc_u32 s1, s5, 0
	v_cndmask_b32_e32 v2, v202, v2, vcc
	v_lshlrev_b32_e32 v213, 2, v2
	v_xor_b32_e32 v2, 4, v202
	v_cmp_lt_i32_e32 vcc, v2, v8
	s_add_u32 s26, s4, 0x3f080000
	s_addc_u32 s27, s5, 0
	v_cndmask_b32_e32 v2, v202, v2, vcc
	v_lshlrev_b32_e32 v214, 2, v2
	v_xor_b32_e32 v2, 8, v202
	v_cmp_lt_i32_e32 vcc, v2, v8
	s_ashr_i32 s3, s2, 6
	s_lshl_b32 s40, s3, 5
	v_cndmask_b32_e32 v2, v202, v2, vcc
	v_lshlrev_b32_e32 v215, 2, v2
	v_xor_b32_e32 v2, 16, v202
	v_cmp_lt_i32_e32 vcc, v2, v8
	s_cmp_lt_u32 s2, 64
	s_cselect_b64 s[4:5], -1, 0
	v_cndmask_b32_e32 v2, v202, v2, vcc
	v_lshlrev_b32_e32 v216, 2, v2
	v_ashrrev_i32_e32 v2, 31, v177
	v_writelane_b32 v245, s4, 30
	v_lshrrev_b32_e32 v2, 28, v2
	s_add_i32 s2, 0, 0x12a00
	v_writelane_b32 v245, s5, 31
	v_cmp_gt_u32_e64 s[4:5], 2, v192
	v_add_u32_e32 v2, v177, v2
	v_add_u32_e32 v194, s2, v3
	v_writelane_b32 v245, s4, 32
	v_ashrrev_i32_e32 v3, 4, v2
	v_and_b32_e32 v2, -16, v2
	v_writelane_b32 v245, s5, 33
	v_cmp_gt_u32_e64 s[4:5], 4, v192
	v_sub_u32_e32 v2, v177, v2
	v_lshlrev_b32_e32 v6, 3, v2
	v_writelane_b32 v245, s4, 34
	v_lshl_add_u32 v178, v3, 11, v6
	v_add_u32_e32 v6, 0x200, v177
	v_writelane_b32 v245, s5, 35
	v_cmp_gt_u32_e64 s[4:5], 8, v192
	v_ashrrev_i32_e32 v7, 31, v6
	v_lshlrev_b32_e32 v4, 7, v177
	v_writelane_b32 v245, s4, 36
	v_and_b32_e32 v5, 0x78, v5
	v_lshrrev_b32_e32 v7, 28, v7
	v_writelane_b32 v245, s5, 37
	s_movk_i32 s4, 0xf800
	s_lshl_b32 s2, s3, 2
	s_movk_i32 s3, 0x140
	v_add_u32_e32 v7, v6, v7
	v_and_or_b32 v182, v4, s4, v5
	v_lshrrev_b32_e32 v4, 4, v177
	v_and_b32_e32 v193, 31, v177
	s_add_i32 s41, s2, 0
	s_movk_i32 s2, 0x110
	v_ashrrev_i32_e32 v8, 4, v7
	v_and_b32_e32 v7, -16, v7
	v_mul_lo_u32 v221, v4, s3
	v_lshrrev_b32_e32 v4, 4, v6
	v_sub_u32_e32 v7, v6, v7
	v_mul_lo_u32 v217, v3, s2
	v_mul_lo_u32 v219, v8, s2
	v_mul_lo_u32 v222, v4, s3
	v_or_b32_e32 v4, s40, v193
	v_mov_b32_e32 v1, 0
	v_lshlrev_b32_e32 v9, 3, v7
	v_add_u32_e32 v3, 0, v217
	v_lshlrev_b32_e32 v218, 4, v2
	v_add_u32_e32 v2, 0, v219
	v_lshlrev_b32_e32 v220, 4, v7
	v_sub_u32_e32 v4, v4, v176
	s_add_i32 s2, 0, 0x12c10
	s_mov_b32 s25, 0
	v_cmp_eq_u32_e64 s[6:7], 0, v192
	v_cmp_gt_i32_e64 s[44:45], 64, v177
	v_add_u32_e32 v197, 0, v196
	v_lshlrev_b32_e32 v198, 2, v177
	s_add_i32 s41, s41, 0x12c20
	v_mul_u32_u24_e32 v199, 0x110, v193
	v_cmp_gt_u32_e64 s[52:53], 16, v192
	v_cmp_gt_u32_e64 s[54:55], 32, v192
	v_lshl_add_u32 v180, v8, 11, v9
	v_add_u32_e32 v184, 0x10000, v182
	v_mov_b32_e32 v179, v1
	v_mov_b32_e32 v181, v1
	v_mov_b32_e32 v183, v1
	v_mov_b32_e32 v185, v1
	v_add_u32_e32 v223, 0xffffff40, v4
	v_lshlrev_b32_e32 v186, 1, v0
	s_add_i32 s42, 0, 0x12c00
	v_writelane_b32 v245, s2, 38
	v_add_u32_e32 v224, v3, v218
	v_add_u32_e32 v225, v2, v220
	v_mov_b32_e32 v226, 0x260
	v_lshlrev_b32_e32 v188, 1, v176
	v_mov_b32_e32 v232, v1
	v_mov_b32_e32 v233, v1
	v_mov_b32_e32 v234, v1
	v_mov_b32_e32 v235, v1
	v_mov_b32_e32 v227, 0xff800000
	s_mov_b32 s2, s96
	s_mov_b32 s43, s96
	s_branch .LBB0_2744

; template <int DQK, bool FOX>
; __device__ __forceinline__ void causal_attn_phase(LAS unsigned char* lds, const bf16_t* Q, int qpitch, const bf16_t* K1, const bf16_t* K2, const bf16_t* V, bf16_t* O, const float* cum2, const float* rope_cs_tab, const float* fox_ct) {
;     ...
;         const int rnd = u >> 8, bb = u & 255, head = bb & 15, qb = rnd == 0 ? 31 - (bb >> 4) : (bb >> 4);
;         const int q0 = qb * 256, qrow = q0 + wid * 32 + r32;
;         bf16x8 qf[NKS];
;         { const bf16_t* qp = Q + (size_t)qrow * qpitch + head * DQK + hi * 8;
; #pragma unroll
;           for (int ks = 0; ks < NKS; ++ks) qf[ks] = *(const bf16x8*)(qp + ks * 16); }
.LBB0_2744:
	s_lshr_b32 s3, s43, 4
	s_and_b32 s10, s43, 15
	s_sub_i32 s3, 31, s3
	s_bfe_u32 s4, s43, 0x40004
	s_cmpk_lt_u32 s43, 0x100
	s_cselect_b32 s8, s3, s4
	s_cbranch_scc1 .Lfox_r0a
	v_readlane_b32 s98, v247, s10
	s_and_b32 s98, s98, 0xff
	s_sub_i32 s98, 15, s98
	v_readlane_b32 s99, v247, s98
	s_bfe_u32 s10, s99, 0x80008
.Lfox_r0a:
	s_lshl_b32 s9, s8, 8
	s_add_i32 s35, s9, s40
	v_or_b32_e32 v2, s35, v193
	v_ashrrev_i32_e32 v3, 31, v2
	v_lshlrev_b64 v[190:191], 12, v[2:3]
	v_lshl_add_u64 v[2:3], s[30:31], 0, v[190:191]
	s_lshl_b32 s24, s10, 8
	v_lshl_add_u64 v[2:3], v[2:3], 0, s[24:25]
	v_mov_b32_e32 v187, v1
	v_lshl_add_u64 v[2:3], v[2:3], 0, v[186:187]
	global_load_dwordx4 v[128:131], v[2:3], off
	global_load_dwordx4 v[132:135], v[2:3], off offset:32
	global_load_dwordx4 v[136:139], v[2:3], off offset:64
	global_load_dwordx4 v[140:143], v[2:3], off offset:96
	global_load_dwordx4 v[144:147], v[2:3], off offset:128
	global_load_dwordx4 v[148:151], v[2:3], off offset:160
	global_load_dwordx4 v[152:155], v[2:3], off offset:192
	global_load_dwordx4 v[156:159], v[2:3], off offset:224
	v_readlane_b32 s4, v245, 30
	v_readlane_b32 s5, v245, 31
	s_andn2_b64 vcc, exec, s[4:5]
	s_lshl_b32 s3, s10, 7
	s_cbranch_vccnz .LBB0_2748
	v_or_b32_e32 v0, s3, v192
	v_lshlrev_b32_e32 v0, 2, v0
	global_load_dword v4, v0, s[26:27]
	global_load_dword v5, v0, s[26:27] offset:256
	v_lshl_add_u64 v[2:3], s[26:27], 0, v[0:1]
	s_mov_b32 s4, 0x8000
	v_add_co_u32_e32 v2, vcc, s4, v2
	v_readlane_b32 s4, v245, 32
	s_nop 0
	v_addc_co_u32_e32 v3, vcc, 0, v3, vcc
	global_load_dword v0, v[2:3], off offset:256
	s_nop 0
	global_load_dword v2, v[2:3], off
	v_readlane_b32 s5, v245, 33
	s_waitcnt vmcnt(3)
	ds_bpermute_b32 v3, v205, v4
	s_waitcnt vmcnt(2)
	ds_bpermute_b32 v6, v205, v5
	s_waitcnt lgkmcnt(1)
	v_add_f32_e32 v3, v4, v3
	v_cndmask_b32_e64 v3, v3, v4, s[6:7]
	ds_bpermute_b32 v7, v206, v3
	s_waitcnt vmcnt(1)
	v_max_f32_e32 v0, v0, v0
	s_waitcnt vmcnt(0)
	v_max_f32_e32 v2, v2, v2
	v_max_f32_e32 v0, v2, v0
	ds_bpermute_b32 v2, v212, v0
	s_waitcnt lgkmcnt(2)
	v_add_f32_e32 v6, v5, v6
	v_cndmask_b32_e64 v6, v6, v5, s[6:7]
	ds_bpermute_b32 v8, v206, v6
	s_waitcnt lgkmcnt(2)
	v_add_f32_e32 v7, v3, v7
	v_cndmask_b32_e64 v3, v7, v3, s[4:5]
	s_waitcnt lgkmcnt(1)
	v_max_f32_e32 v2, v2, v2
	ds_bpermute_b32 v7, v207, v3
	v_max_f32_e32 v0, v0, v2
	ds_bpermute_b32 v2, v213, v0
	s_waitcnt lgkmcnt(2)
	v_add_f32_e32 v8, v6, v8
	v_cndmask_b32_e64 v6, v8, v6, s[4:5]
	ds_bpermute_b32 v8, v207, v6
	v_readlane_b32 s4, v245, 34
	s_waitcnt lgkmcnt(2)
	v_add_f32_e32 v7, v3, v7
	v_readlane_b32 s5, v245, 35
	s_waitcnt lgkmcnt(1)
	v_max_f32_e32 v2, v2, v2
	v_max_f32_e32 v0, v0, v2
	v_cndmask_b32_e64 v3, v7, v3, s[4:5]
	ds_bpermute_b32 v7, v208, v3
	ds_bpermute_b32 v2, v214, v0
	s_waitcnt lgkmcnt(2)
	v_add_f32_e32 v8, v6, v8
	v_cndmask_b32_e64 v6, v8, v6, s[4:5]
	ds_bpermute_b32 v8, v208, v6
	v_readlane_b32 s4, v245, 36
	s_waitcnt lgkmcnt(2)
	v_add_f32_e32 v7, v3, v7
	v_readlane_b32 s5, v245, 37
	s_waitcnt lgkmcnt(1)
	v_max_f32_e32 v2, v2, v2
	v_max_f32_e32 v0, v0, v2
	v_cndmask_b32_e64 v3, v7, v3, s[4:5]
	ds_bpermute_b32 v7, v209, v3
	ds_bpermute_b32 v2, v215, v0
	s_waitcnt lgkmcnt(2)
	v_add_f32_e32 v8, v6, v8
	v_cndmask_b32_e64 v6, v8, v6, s[4:5]
	ds_bpermute_b32 v8, v209, v6
	s_waitcnt lgkmcnt(2)
	v_add_f32_e32 v7, v3, v7
	v_cndmask_b32_e64 v3, v7, v3, s[52:53]
	s_waitcnt lgkmcnt(1)
	v_max_f32_e32 v2, v2, v2
	ds_bpermute_b32 v7, v210, v3
	v_max_f32_e32 v0, v0, v2
	ds_bpermute_b32 v2, v216, v0
	s_waitcnt lgkmcnt(2)
	v_add_f32_e32 v8, v6, v8
	v_cndmask_b32_e64 v6, v8, v6, s[52:53]
	ds_bpermute_b32 v8, v210, v6
	s_waitcnt lgkmcnt(2)
	v_add_f32_e32 v7, v3, v7
	v_cndmask_b32_e64 v3, v7, v3, s[54:55]
	s_waitcnt lgkmcnt(1)
	v_max_f32_e32 v2, v2, v2
	ds_bpermute_b32 v7, v211, v3
	v_max_f32_e32 v0, v0, v2
	ds_bpermute_b32 v2, v195, v0
	s_waitcnt lgkmcnt(2)
	v_add_f32_e32 v8, v6, v8
	v_cndmask_b32_e64 v6, v8, v6, s[54:55]
	v_sub_f32_e32 v3, v3, v4
	v_sub_f32_e32 v4, v6, v5
	s_waitcnt lgkmcnt(1)
	v_add_f32_e32 v4, v4, v7
	ds_write2st64_b32 v194, v3, v4 offset1:1
	s_and_saveexec_b64 s[4:5], s[6:7]
	s_cbranch_execz .LBB0_2747
	s_waitcnt lgkmcnt(1)
	v_max_f32_e32 v2, v2, v2
	v_max_f32_e32 v0, v0, v0
	v_max_f32_e32 v0, v0, v2
	v_mov_b32_e32 v2, s42
	v_readlane_b32 s11, v245, 38
	ds_write_b32 v2, v0
	s_nop 0
	v_mov_b32_e32 v0, s11
	ds_write_b128 v0, v[232:235]

; #define LAS __attribute__((address_space(3)))
; __device__ __forceinline__ float bf2f(unsigned short u) { return __uint_as_float((unsigned)u << 16); }
; template <int DQK, bool FOX>
; __device__ __forceinline__ void causal_attn_phase(LAS unsigned char* lds, const bf16_t* Q, int qpitch, const bf16_t* K1, const bf16_t* K2, const bf16_t* V, bf16_t* O, const float* cum2, const float* rope_cs_tab, const float* fox_ct) {
;     ...
;             float qn = 0.f;
; #pragma unroll
;             for (int ks = 0; ks < NKS; ++ks)
; #pragma unroll
;                 for (int j = 0; j < 8; ++j) { const float a = bf2f((unsigned short)qf[ks][j]); qn += a * a; }
;             qn += __shfl_xor(qn, 32);
;             qn = sqrtf(qn) * offs[128] * 1.02f + 1.0f;
;             volatile LAS int* dflag = (volatile LAS int*)(offs + 136);
;             bool done = false;
;             CA_GLOAD(NT - 1); CA_LSTORE(0); __syncthreads();
;             for (int tt = 0; tt < NT; ++tt) {
.LBB0_2750:
	s_or_b64 exec, exec, s[4:5]
	v_add_u32_e32 v4, v197, v221
	s_waitcnt vmcnt(3)
	ds_write_b128 v224, v[160:163]
	s_waitcnt vmcnt(2)
	ds_write_b128 v225, v[164:167]
	s_waitcnt vmcnt(1)
	ds_write_b128 v4, v[168:171] offset:17408
	v_add_u32_e32 v4, v197, v222
	s_waitcnt vmcnt(0)
	ds_write_b128 v4, v[172:175] offset:17408
	s_and_saveexec_b64 s[4:5], s[44:45]
	v_add_u32_e32 v4, 0, v198
	ds_write_b32 v4, v187 offset:37888
	s_or_b64 exec, exec, s[4:5]
	s_waitcnt lgkmcnt(5)
	v_add_f32_e32 v0, v0, v3
	s_mov_b32 s4, 0xf800000
	v_mul_f32_e32 v3, 0x4f800000, v0
	v_cmp_gt_f32_e32 vcc, s4, v0
	s_mov_b32 s4, 0x3f828f5c
	v_mov_b32_e32 v14, v1
	v_cndmask_b32_e32 v0, v0, v3, vcc
	v_sqrt_f32_e32 v3, v0
	v_mov_b32_e32 v15, v1
	v_mov_b32_e32 v6, v1
	v_mov_b32_e32 v7, v1
	v_add_u32_e32 v4, -1, v3
	v_fma_f32 v5, -v4, v3, v0
	v_cmp_ge_f32_e64 s[56:57], 0, v5
	v_add_u32_e32 v5, 1, v3
	v_mov_b32_e32 v8, v1
	v_cndmask_b32_e64 v4, v3, v4, s[56:57]
	v_fma_f32 v3, -v5, v3, v0
	v_cmp_lt_f32_e64 s[56:57], 0, v3
	v_mov_b32_e32 v9, v1
	v_mov_b32_e32 v10, v1
	v_cndmask_b32_e64 v3, v4, v5, s[56:57]
	v_mul_f32_e32 v4, 0x37800000, v3
	v_cndmask_b32_e32 v3, v3, v4, vcc
	v_cmp_class_f32_e32 vcc, v0, v226
	v_mov_b32_e32 v4, v1
	v_mov_b32_e32 v5, v1
	v_cndmask_b32_e32 v0, v3, v0, vcc
	s_waitcnt lgkmcnt(4)
	v_mul_f32_e32 v0, v2, v0
	v_fma_f32 v189, v0, s4, 1.0
	s_and_b32 s4, s2, 15
	s_cmpk_lt_u32 s2, 0x100
	s_cbranch_scc1 .Lfox_h0
	v_readlane_b32 s98, v247, s4
	s_and_b32 s98, s98, 0xff
	s_sub_i32 s98, 15, s98
	v_readlane_b32 s99, v247, s98
	s_bfe_u32 s4, s99, 0x80008

; __global__ void __launch_bounds__(512) mega_fwd(Params p_unused) {
	.amdhsa_kernel _Z8mega_fwd6Params
		.amdhsa_group_segment_fixed_size 0
		.amdhsa_private_segment_fixed_size 0
		.amdhsa_kernarg_size 480
		.amdhsa_user_sgpr_count 2
		.amdhsa_user_sgpr_dispatch_ptr 0
		.amdhsa_user_sgpr_queue_ptr 0
		.amdhsa_user_sgpr_kernarg_segment_ptr 1
		.amdhsa_user_sgpr_dispatch_id 0
		.amdhsa_user_sgpr_kernarg_preload_length 0
		.amdhsa_user_sgpr_kernarg_preload_offset 0
		.amdhsa_user_sgpr_private_segment_size 0
		.amdhsa_uses_dynamic_stack 0
		.amdhsa_enable_private_segment 0
		.amdhsa_system_sgpr_workgroup_id_x 1
		.amdhsa_system_sgpr_workgroup_id_y 0
		.amdhsa_system_sgpr_workgroup_id_z 0
		.amdhsa_system_sgpr_workgroup_info 0
		.amdhsa_system_vgpr_workitem_id 2
		.amdhsa_next_free_vgpr 248
		.amdhsa_next_free_sgpr 102
		.amdhsa_accum_offset 248
		.amdhsa_reserve_vcc 1
		.amdhsa_float_round_mode_32 0
		.amdhsa_float_round_mode_16_64 0
		.amdhsa_float_denorm_mode_32 3
		.amdhsa_float_denorm_mode_16_64 3
		.amdhsa_dx10_clamp 1
		.amdhsa_ieee_mode 1
		.amdhsa_fp16_overflow 0
		.amdhsa_tg_split 0
		.amdhsa_exception_fp_ieee_invalid_op 0
		.amdhsa_exception_fp_denorm_src 0
		.amdhsa_exception_fp_ieee_div_zero 0
		.amdhsa_exception_fp_ieee_overflow 0
		.amdhsa_exception_fp_ieee_underflow 0
		.amdhsa_exception_fp_ieee_inexact 0
		.amdhsa_exception_int_div_zero 0
	.end_amdhsa_kernel

; __global__ void __launch_bounds__(512) mega_fwd(Params p_unused) {
amdhsa.kernels:
  - .agpr_count:     0
    .args:
      - .offset:         0
        .size:           224
        .value_kind:     by_value
      - .offset:         224
        .size:           4
        .value_kind:     hidden_block_count_x
      - .offset:         228
        .size:           4
        .value_kind:     hidden_block_count_y
      - .offset:         232
        .size:           4
        .value_kind:     hidden_block_count_z
      - .offset:         236
        .size:           2
        .value_kind:     hidden_group_size_x
      - .offset:         238
        .size:           2
        .value_kind:     hidden_group_size_y
      - .offset:         240
        .size:           2
        .value_kind:     hidden_group_size_z
      - .offset:         242
        .size:           2
        .value_kind:     hidden_remainder_x
      - .offset:         244
        .size:           2
        .value_kind:     hidden_remainder_y
      - .offset:         246
        .size:           2
        .value_kind:     hidden_remainder_z
      - .offset:         264
        .size:           8
        .value_kind:     hidden_global_offset_x
      - .offset:         272
        .size:           8
        .value_kind:     hidden_global_offset_y
      - .offset:         280
        .size:           8
        .value_kind:     hidden_global_offset_z
      - .offset:         288
        .size:           2
        .value_kind:     hidden_grid_dims
      - .offset:         312
        .size:           8
        .value_kind:     hidden_multigrid_sync_arg
      - .offset:         344
        .size:           4
        .value_kind:     hidden_dynamic_lds_size
    .group_segment_fixed_size: 0
    .kernarg_segment_align: 8
    .kernarg_segment_size: 480
    .language:       OpenCL C
    .language_version:
      - 2
      - 0
    .max_flat_workgroup_size: 512
    .name:           _Z8mega_fwd6Params
    .private_segment_fixed_size: 0
    .sgpr_count:     108
    .sgpr_spill_count: 109
    .symbol:         _Z8mega_fwd6Params.kd
    .uniform_work_group_size: 1
    .uses_dynamic_stack: false
    .vgpr_count:     248
    .vgpr_spill_count: 0
    .wavefront_size: 64
